# grid barrier: generation from the phase index instead of two integer divisions; no L2 write-back after the all-write-through residual phases
# speedup vs baseline: 1.0047x; 1.0047x over previous
; __device__ __forceinline__ unsigned xb_add(unsigned* p, unsigned v) { return __hip_atomic_fetch_add(p, v, __ATOMIC_RELAXED, __HIP_MEMORY_SCOPE_AGENT); }
; __device__ __forceinline__ void xcd_barrier(const XcdBarrier& b) {
;     ...
;         const unsigned old = xb_add(&bar[XB_XSUB(b.x)], 1u);
;         const unsigned gen = old / nloc;
;         if (old + 1u == (gen + 1u) * nloc) {
.LBB0_40:
	s_or_b64 exec, exec, s[10:11]
	s_sub_i32 s14, s47, s48
	s_add_i32 s14, s14, -1
	s_waitcnt vmcnt(0)
	v_readfirstlane_b32 s3, v4
	v_add_u32_e32 v6, s3, v2
	v_add_u32_e32 v4, 1, v6
	v_mov_b32_e32 v2, s14
	s_nop 0
	v_mad_u32_u24 v3, v3, v2, v3
	v_cmp_ne_u32_e32 vcc, v4, v3
	s_and_saveexec_b64 s[10:11], vcc
	s_xor_b64 s[10:11], exec, s[10:11]
	s_cbranch_execz .LBB0_54
	v_readlane_b32 s14, v252, 10
	v_readlane_b32 s15, v252, 11
	s_waitcnt lgkmcnt(0)
	s_nop 3
	global_load_dword v0, v1, s[14:15] sc1
	s_waitcnt vmcnt(0)
	v_cmp_eq_u32_e32 vcc, v0, v2
	s_and_saveexec_b64 s[16:17], vcc
	s_cbranch_execz .LBB0_53
	s_mov_b32 s3, 1
	s_mov_b64 s[18:19], 0
	s_branch .LBB0_44

; __device__ __forceinline__ unsigned xb_add(unsigned* p, unsigned v) { return __hip_atomic_fetch_add(p, v, __ATOMIC_RELAXED, __HIP_MEMORY_SCOPE_AGENT); }
; __device__ __forceinline__ void xcd_barrier(const XcdBarrier& b) {
;     ...
;             const unsigned og = xb_add(&bar[XB_TOP], 1u);
;             const unsigned tg = og / nx;
;             if (og + 1u == (tg + 1u) * nx) xb_add(&bar[XB_TOPGEN], 1u);
.LBB0_57:
	s_or_b64 exec, exec, s[16:17]
	s_sub_i32 s14, s47, s48
	s_add_i32 s14, s14, -1
	s_waitcnt vmcnt(0)
	v_readfirstlane_b32 s3, v3
	v_readlane_b32 s10, v252, 14
	v_readlane_b32 s11, v252, 15
	v_add_u32_e32 v2, s3, v2
	v_add_u32_e32 v5, 1, v2
	v_mov_b32_e32 v4, s14
	s_mov_b64 s[16:17], -1
	v_mad_u32_u24 v0, v0, v4, v0
	v_cmp_ne_u32_e32 vcc, v5, v0
	v_mov_b64_e32 v[2:3], s[10:11]
	s_and_saveexec_b64 s[10:11], vcc
	s_cbranch_execz .Lxb_last
	v_readlane_b32 s14, v252, 10
	v_readlane_b32 s15, v252, 11
	s_mov_b64 s[18:19], 0
	s_nop 3
	global_load_dword v0, v1, s[14:15] sc1
	s_waitcnt vmcnt(0)
	v_cmp_eq_u32_e32 vcc, v0, v4
	s_and_saveexec_b64 s[16:17], vcc
	s_cbranch_execz .LBB0_68
	s_mov_b32 s3, 1
	s_branch .LBB0_61
